# l=1 post phase: two tiles per workgroup software-pipelined, waits count every younger VMEM op (stores no longer drained before loads)
# speedup vs baseline: 1.0226x; 1.0018x over previous
; DI float lo16(unsigned u) { return __uint_as_float(u << 16); }
; DI float hi16(unsigned u) { return __uint_as_float(u & 0xFFFF0000u); }
; DI int osgpr(int v) { asm volatile("" : "+s"(v)); return v; }
; DI void post_phase(const P& p, int l, unsigned char* smem, int t0, int t1, int bstart, int bstride) {
;     ...
;     for (int rt = t0 + osgpr(bstart); rt < t1; rt += bstride) {
;       for (int rr = 0; rr < 2; ++rr) {
;         const int row = rt * 16 + wave * 2 + rr;
;         const int mr = row < NLAT ? (row >> 11) : 4;
;         const float* h = l == 0 ? (row < NLAT ? p.x + (size_t)row * DM : p.ctx + (size_t)(row - NLAT) * DM) : p.out + (size_t)row * DM;
;         float* hdst = row < NLAT ? p.out + (size_t)row * DM : hc + (size_t)(row - NLAT) * DM;
;         f32x4 y[8]; float ss = 0.f;
; #pragma unroll
;         for (int i = 0; i < 8; ++i) {
;             const u32x2 w = __builtin_nontemporal_load((const u32x2*)(yo + (size_t)row * DM + i * 256 + lane * 4));
;             y[i] = (f32x4){lo16(w.x), hi16(w.x), lo16(w.y), hi16(w.y)};
;             ss += y[i][0] * y[i][0] + y[i][1] * y[i][1] + y[i][2] * y[i][2] + y[i][3] * y[i][3];
;         }
;         ss = wave_sum(ss);
;         const float rstd = rsqrtf(ss * (1.f / 2048.f) + 1e-6f);
;         const float* md = mod + (size_t)(l * 5 + mr) * 6144;
;         float ss2 = 0.f;
; #pragma unroll
;         for (int i = 0; i < 8; ++i) {
;             const int j = i * 256 + lane * 4;
;             const f32x4 hv = __builtin_nontemporal_load((const f32x4*)(h + j)), gt = *(const f32x4*)(md + 4096 + j), nw = *(const f32x4*)(p.norm_post + l * DM + j);
; #pragma unroll
;             for (int e = 0; e < 4; ++e) { y[i][e] = hv[e] + gt[e] * (y[i][e] * rstd * nw[e]); ss2 += y[i][e] * y[i][e]; }
;             __builtin_nontemporal_store(y[i], (f32x4*)(hdst + j));
;         }
.Lp1_pair:
	s_add_u32 s3, s2, s10
	s_cmpk_lt_i32 s3, 0x200
	s_cbranch_scc0 .Lp1_single
	s_lshl_b32 s12, s2, 4
	s_add_u32 s12, s12, s11
	s_lshl_b32 s14, s12, 12
	s_add_u32 s14, s14, 0x6c3c000
	s_add_u32 s14, s4, s14
	s_addc_u32 s15, s5, 0
	s_lshl_b32 s16, s12, 13
	s_add_u32 s16, s6, s16
	s_addc_u32 s17, s7, 0
	s_add_u32 s18, s16, 0x2000
	s_addc_u32 s19, s17, 0
	s_lshr_b32 s20, s12, 11
	s_add_u32 s20, s20, 5
	s_mul_i32 s20, s20, 0x6000
	s_add_u32 s20, s20, 0x4804000
	s_add_u32 s20, s4, s20
	s_addc_u32 s21, s5, 0
	s_lshl_b32 s13, s3, 4
	s_add_u32 s13, s13, s11
	s_lshl_b32 s22, s13, 12
	s_add_u32 s22, s22, 0x6c3c000
	s_add_u32 s22, s4, s22
	s_addc_u32 s23, s5, 0
	s_lshl_b32 s24, s13, 13
	s_add_u32 s24, s6, s24
	s_addc_u32 s25, s7, 0
	s_add_u32 s26, s24, 0x2000
	s_addc_u32 s27, s25, 0
	s_lshr_b32 s28, s13, 11
	s_add_u32 s28, s28, 5
	s_mul_i32 s28, s28, 0x6000
	s_add_u32 s28, s28, 0x4804000
	s_add_u32 s28, s4, s28
	s_addc_u32 s29, s5, 0
	global_load_dwordx2 v[52:53], v2, s[14:15] offset:0 nt
	global_load_dwordx2 v[54:55], v2, s[14:15] offset:512 nt
	global_load_dwordx2 v[56:57], v2, s[14:15] offset:1024 nt
	global_load_dwordx2 v[58:59], v2, s[14:15] offset:1536 nt
	global_load_dwordx2 v[60:61], v2, s[14:15] offset:2048 nt
	global_load_dwordx2 v[62:63], v2, s[14:15] offset:2560 nt
	global_load_dwordx2 v[64:65], v2, s[14:15] offset:3072 nt
	global_load_dwordx2 v[66:67], v2, s[14:15] offset:3584 nt
	global_load_dwordx2 v[68:69], v17, s[14:15] offset:0 nt
	global_load_dwordx2 v[70:71], v17, s[14:15] offset:512 nt
	global_load_dwordx2 v[72:73], v17, s[14:15] offset:1024 nt
	global_load_dwordx2 v[74:75], v17, s[14:15] offset:1536 nt
	global_load_dwordx2 v[76:77], v17, s[14:15] offset:2048 nt
	global_load_dwordx2 v[78:79], v17, s[14:15] offset:2560 nt
	global_load_dwordx2 v[80:81], v17, s[14:15] offset:3072 nt
	global_load_dwordx2 v[82:83], v17, s[14:15] offset:3584 nt
	global_load_dwordx4 v[116:119], v0, s[20:21] offset:0
	global_load_dwordx4 v[120:123], v0, s[20:21] offset:1024
	global_load_dwordx4 v[124:127], v0, s[20:21] offset:2048
	global_load_dwordx4 v[128:131], v0, s[20:21] offset:3072
	global_load_dwordx4 v[132:135], v1, s[20:21] offset:0
	global_load_dwordx4 v[136:139], v1, s[20:21] offset:1024
	global_load_dwordx4 v[140:143], v1, s[20:21] offset:2048
	global_load_dwordx4 v[144:147], v1, s[20:21] offset:3072
	global_load_dwordx4 v[84:87], v0, s[16:17] offset:0 nt
	global_load_dwordx4 v[88:91], v0, s[16:17] offset:1024 nt
	global_load_dwordx4 v[92:95], v0, s[16:17] offset:2048 nt
	global_load_dwordx4 v[96:99], v0, s[16:17] offset:3072 nt
	global_load_dwordx4 v[100:103], v1, s[16:17] offset:0 nt
	global_load_dwordx4 v[104:107], v1, s[16:17] offset:1024 nt
	global_load_dwordx4 v[108:111], v1, s[16:17] offset:2048 nt
	global_load_dwordx4 v[112:115], v1, s[16:17] offset:3072 nt
	global_load_dwordx4 v[148:151], v0, s[18:19] offset:0 nt
	global_load_dwordx4 v[152:155], v0, s[18:19] offset:1024 nt
	global_load_dwordx4 v[156:159], v0, s[18:19] offset:2048 nt
	global_load_dwordx4 v[160:163], v0, s[18:19] offset:3072 nt
	global_load_dwordx4 v[164:167], v1, s[18:19] offset:0 nt
	global_load_dwordx4 v[168:171], v1, s[18:19] offset:1024 nt
	global_load_dwordx4 v[172:175], v1, s[18:19] offset:2048 nt
	global_load_dwordx4 v[176:179], v1, s[18:19] offset:3072 nt
	s_waitcnt vmcnt(24)
	global_load_dwordx2 v[180:181], v2, s[22:23] offset:0 nt
	global_load_dwordx2 v[182:183], v2, s[22:23] offset:512 nt
	global_load_dwordx2 v[184:185], v2, s[22:23] offset:1024 nt
	global_load_dwordx2 v[186:187], v2, s[22:23] offset:1536 nt
	global_load_dwordx2 v[188:189], v2, s[22:23] offset:2048 nt
	global_load_dwordx2 v[190:191], v2, s[22:23] offset:2560 nt
	global_load_dwordx2 v[192:193], v2, s[22:23] offset:3072 nt
	global_load_dwordx2 v[194:195], v2, s[22:23] offset:3584 nt
	global_load_dwordx2 v[196:197], v17, s[22:23] offset:0 nt
	global_load_dwordx2 v[198:199], v17, s[22:23] offset:512 nt
	global_load_dwordx2 v[200:201], v17, s[22:23] offset:1024 nt
	global_load_dwordx2 v[202:203], v17, s[22:23] offset:1536 nt
	global_load_dwordx2 v[204:205], v17, s[22:23] offset:2048 nt
	global_load_dwordx2 v[206:207], v17, s[22:23] offset:2560 nt
	global_load_dwordx2 v[208:209], v17, s[22:23] offset:3072 nt
	global_load_dwordx2 v[210:211], v17, s[22:23] offset:3584 nt
	global_load_dwordx4 v[216:219], v0, s[28:29] offset:0
	global_load_dwordx4 v[220:223], v0, s[28:29] offset:1024
	global_load_dwordx4 v[224:227], v0, s[28:29] offset:2048
	global_load_dwordx4 v[228:231], v0, s[28:29] offset:3072
	global_load_dwordx4 v[232:235], v1, s[28:29] offset:0
	global_load_dwordx4 v[236:239], v1, s[28:29] offset:1024
	global_load_dwordx4 v[240:243], v1, s[28:29] offset:2048
	global_load_dwordx4 v[244:247], v1, s[28:29] offset:3072
	v_lshlrev_b32_e32 v212, 16, v52
	v_and_b32_e32 v213, 0xffff0000, v52
	v_lshlrev_b32_e32 v214, 16, v53
	v_and_b32_e32 v215, 0xffff0000, v53
	v_mul_f32_e32 v9, v212, v212
	v_mul_f32_e32 v15, v213, v213
	v_fmac_f32_e32 v9, v214, v214
	v_fmac_f32_e32 v15, v215, v215
	v_lshlrev_b32_e32 v212, 16, v54
	v_and_b32_e32 v213, 0xffff0000, v54
	v_lshlrev_b32_e32 v214, 16, v55
	v_and_b32_e32 v215, 0xffff0000, v55
	v_fmac_f32_e32 v9, v212, v212
	v_fmac_f32_e32 v15, v213, v213
	v_fmac_f32_e32 v9, v214, v214
	v_fmac_f32_e32 v15, v215, v215
	v_lshlrev_b32_e32 v212, 16, v56
	v_and_b32_e32 v213, 0xffff0000, v56
	v_lshlrev_b32_e32 v214, 16, v57
	v_and_b32_e32 v215, 0xffff0000, v57
	v_fmac_f32_e32 v9, v212, v212
	v_fmac_f32_e32 v15, v213, v213
	v_fmac_f32_e32 v9, v214, v214
	v_fmac_f32_e32 v15, v215, v215
	v_lshlrev_b32_e32 v212, 16, v58
	v_and_b32_e32 v213, 0xffff0000, v58
; DI float lo16(unsigned u) { return __uint_as_float(u << 16); }
; DI float hi16(unsigned u) { return __uint_as_float(u & 0xFFFF0000u); }
; DI void post_phase(const P& p, int l, unsigned char* smem, int t0, int t1, int bstart, int bstride) {
;     ...
;         f32x4 y[8]; float ss = 0.f;
; #pragma unroll
;         for (int i = 0; i < 8; ++i) {
;             const u32x2 w = __builtin_nontemporal_load((const u32x2*)(yo + (size_t)row * DM + i * 256 + lane * 4));
;             y[i] = (f32x4){lo16(w.x), hi16(w.x), lo16(w.y), hi16(w.y)};
;             ss += y[i][0] * y[i][0] + y[i][1] * y[i][1] + y[i][2] * y[i][2] + y[i][3] * y[i][3];
;         }
;         ss = wave_sum(ss);
;         const float rstd = rsqrtf(ss * (1.f / 2048.f) + 1e-6f);
;         const float* md = mod + (size_t)(l * 5 + mr) * 6144;
;         float ss2 = 0.f;
; #pragma unroll
;         for (int i = 0; i < 8; ++i) {
;             const int j = i * 256 + lane * 4;
;             const f32x4 hv = __builtin_nontemporal_load((const f32x4*)(h + j)), gt = *(const f32x4*)(md + 4096 + j), nw = *(const f32x4*)(p.norm_post + l * DM + j);
; #pragma unroll
;             for (int e = 0; e < 4; ++e) { y[i][e] = hv[e] + gt[e] * (y[i][e] * rstd * nw[e]); ss2 += y[i][e] * y[i][e]; }
;             __builtin_nontemporal_store(y[i], (f32x4*)(hdst + j));
;         }
	v_lshlrev_b32_e32 v214, 16, v59
	v_and_b32_e32 v215, 0xffff0000, v59
	v_fmac_f32_e32 v9, v212, v212
	v_fmac_f32_e32 v15, v213, v213
	v_fmac_f32_e32 v9, v214, v214
	v_fmac_f32_e32 v15, v215, v215
	v_lshlrev_b32_e32 v212, 16, v60
	v_and_b32_e32 v213, 0xffff0000, v60
	v_lshlrev_b32_e32 v214, 16, v61
	v_and_b32_e32 v215, 0xffff0000, v61
	v_fmac_f32_e32 v9, v212, v212
	v_fmac_f32_e32 v15, v213, v213
	v_fmac_f32_e32 v9, v214, v214
	v_fmac_f32_e32 v15, v215, v215
	v_lshlrev_b32_e32 v212, 16, v62
	v_and_b32_e32 v213, 0xffff0000, v62
	v_lshlrev_b32_e32 v214, 16, v63
	v_and_b32_e32 v215, 0xffff0000, v63
	v_fmac_f32_e32 v9, v212, v212
	v_fmac_f32_e32 v15, v213, v213
	v_fmac_f32_e32 v9, v214, v214
	v_fmac_f32_e32 v15, v215, v215
	v_lshlrev_b32_e32 v212, 16, v64
	v_and_b32_e32 v213, 0xffff0000, v64
	v_lshlrev_b32_e32 v214, 16, v65
	v_and_b32_e32 v215, 0xffff0000, v65
	v_fmac_f32_e32 v9, v212, v212
	v_fmac_f32_e32 v15, v213, v213
	v_fmac_f32_e32 v9, v214, v214
	v_fmac_f32_e32 v15, v215, v215
	v_lshlrev_b32_e32 v212, 16, v66
	v_and_b32_e32 v213, 0xffff0000, v66
	v_lshlrev_b32_e32 v214, 16, v67
	v_and_b32_e32 v215, 0xffff0000, v67
	v_fmac_f32_e32 v9, v212, v212
	v_fmac_f32_e32 v15, v213, v213
	v_fmac_f32_e32 v9, v214, v214
	v_fmac_f32_e32 v15, v215, v215
	v_add_f32_e32 v9, v9, v15
	v_lshlrev_b32_e32 v212, 16, v68
	v_and_b32_e32 v213, 0xffff0000, v68
	v_lshlrev_b32_e32 v214, 16, v69
	v_and_b32_e32 v215, 0xffff0000, v69
	v_mul_f32_e32 v10, v212, v212
	v_mul_f32_e32 v16, v213, v213
	v_fmac_f32_e32 v10, v214, v214
	v_fmac_f32_e32 v16, v215, v215
	v_lshlrev_b32_e32 v212, 16, v70
	v_and_b32_e32 v213, 0xffff0000, v70
	v_lshlrev_b32_e32 v214, 16, v71
	v_and_b32_e32 v215, 0xffff0000, v71
	v_fmac_f32_e32 v10, v212, v212
	v_fmac_f32_e32 v16, v213, v213
	v_fmac_f32_e32 v10, v214, v214
	v_fmac_f32_e32 v16, v215, v215
	v_lshlrev_b32_e32 v212, 16, v72
	v_and_b32_e32 v213, 0xffff0000, v72
	v_lshlrev_b32_e32 v214, 16, v73
	v_and_b32_e32 v215, 0xffff0000, v73
	v_fmac_f32_e32 v10, v212, v212
	v_fmac_f32_e32 v16, v213, v213
	v_fmac_f32_e32 v10, v214, v214
	v_fmac_f32_e32 v16, v215, v215
	v_lshlrev_b32_e32 v212, 16, v74
	v_and_b32_e32 v213, 0xffff0000, v74
	v_lshlrev_b32_e32 v214, 16, v75
	v_and_b32_e32 v215, 0xffff0000, v75
	v_fmac_f32_e32 v10, v212, v212
	v_fmac_f32_e32 v16, v213, v213
	v_fmac_f32_e32 v10, v214, v214
	v_fmac_f32_e32 v16, v215, v215
	v_lshlrev_b32_e32 v212, 16, v76
	v_and_b32_e32 v213, 0xffff0000, v76
	v_lshlrev_b32_e32 v214, 16, v77
	v_and_b32_e32 v215, 0xffff0000, v77
	v_fmac_f32_e32 v10, v212, v212
	v_fmac_f32_e32 v16, v213, v213
	v_fmac_f32_e32 v10, v214, v214
	v_fmac_f32_e32 v16, v215, v215
	v_lshlrev_b32_e32 v212, 16, v78
	v_and_b32_e32 v213, 0xffff0000, v78
	v_lshlrev_b32_e32 v214, 16, v79
	v_and_b32_e32 v215, 0xffff0000, v79
	v_fmac_f32_e32 v10, v212, v212
	v_fmac_f32_e32 v16, v213, v213
	v_fmac_f32_e32 v10, v214, v214
	v_fmac_f32_e32 v16, v215, v215
	v_lshlrev_b32_e32 v212, 16, v80
	v_and_b32_e32 v213, 0xffff0000, v80
	v_lshlrev_b32_e32 v214, 16, v81
	v_and_b32_e32 v215, 0xffff0000, v81
	v_fmac_f32_e32 v10, v212, v212
	v_fmac_f32_e32 v16, v213, v213
	v_fmac_f32_e32 v10, v214, v214
	v_fmac_f32_e32 v16, v215, v215
	v_lshlrev_b32_e32 v212, 16, v82
	v_and_b32_e32 v213, 0xffff0000, v82
	v_lshlrev_b32_e32 v214, 16, v83
	v_and_b32_e32 v215, 0xffff0000, v83
	v_fmac_f32_e32 v10, v212, v212
	v_fmac_f32_e32 v16, v213, v213
	v_fmac_f32_e32 v10, v214, v214
	v_fmac_f32_e32 v16, v215, v215
	v_add_f32_e32 v10, v10, v16
	ds_bpermute_b32 v11, v3, v9
	ds_bpermute_b32 v12, v3, v10
	s_waitcnt lgkmcnt(1)
	v_add_f32_e32 v9, v9, v11
	s_waitcnt lgkmcnt(0)
	v_add_f32_e32 v10, v10, v12
	ds_bpermute_b32 v11, v4, v9
	ds_bpermute_b32 v12, v4, v10
	s_waitcnt lgkmcnt(1)
	v_add_f32_e32 v9, v9, v11
	s_waitcnt lgkmcnt(0)
	v_add_f32_e32 v10, v10, v12
	ds_bpermute_b32 v11, v5, v9
	ds_bpermute_b32 v12, v5, v10
	s_waitcnt lgkmcnt(1)
	v_add_f32_e32 v9, v9, v11
	s_waitcnt lgkmcnt(0)
	v_add_f32_e32 v10, v10, v12
	ds_bpermute_b32 v11, v6, v9
	ds_bpermute_b32 v12, v6, v10
	s_waitcnt lgkmcnt(1)
	v_add_f32_e32 v9, v9, v11
	s_waitcnt lgkmcnt(0)
	v_add_f32_e32 v10, v10, v12
	ds_bpermute_b32 v11, v7, v9
	ds_bpermute_b32 v12, v7, v10
	s_waitcnt lgkmcnt(1)
	v_add_f32_e32 v9, v9, v11
	s_waitcnt lgkmcnt(0)
	v_add_f32_e32 v10, v10, v12
	ds_bpermute_b32 v11, v8, v9
	ds_bpermute_b32 v12, v8, v10
	s_waitcnt lgkmcnt(1)
	v_add_f32_e32 v9, v9, v11
	s_waitcnt lgkmcnt(0)
	v_add_f32_e32 v10, v10, v12
	v_mov_b32_e32 v11, 0x358637bd
	v_fmamk_f32 v9, v9, 0x3a000000, v11
	v_fmamk_f32 v10, v10, 0x3a000000, v11
	v_rsq_f32_e32 v13, v9
	v_rsq_f32_e32 v14, v10
	s_nop 0
	v_lshlrev_b32_e32 v212, 16, v52
	v_and_b32_e32 v213, 0xffff0000, v52
	v_lshlrev_b32_e32 v214, 16, v53
	v_and_b32_e32 v215, 0xffff0000, v53
	v_mul_f32_e32 v212, v13, v212
	v_mul_f32_e32 v213, v13, v213
	v_mul_f32_e32 v214, v13, v214
	v_mul_f32_e32 v215, v13, v215
	v_mul_f32_e32 v212, v20, v212
	v_mul_f32_e32 v213, v21, v213
	v_mul_f32_e32 v214, v22, v214
	v_mul_f32_e32 v215, v23, v215
	s_waitcnt vmcnt(39)
	v_fma_f32 v84, v116, v212, v84
	v_fma_f32 v85, v117, v213, v85
	v_fma_f32 v86, v118, v214, v86
	v_fma_f32 v87, v119, v215, v87
	global_store_dwordx4 v0, v[84:87], s[16:17] offset:0 sc1
	v_lshlrev_b32_e32 v212, 16, v54
	v_and_b32_e32 v213, 0xffff0000, v54
	v_lshlrev_b32_e32 v214, 16, v55
	v_and_b32_e32 v215, 0xffff0000, v55
	v_mul_f32_e32 v212, v13, v212
	v_mul_f32_e32 v213, v13, v213
	v_mul_f32_e32 v214, v13, v214
	v_mul_f32_e32 v215, v13, v215
	v_mul_f32_e32 v212, v24, v212
	v_mul_f32_e32 v213, v25, v213
	v_mul_f32_e32 v214, v26, v214
	v_mul_f32_e32 v215, v27, v215
	s_waitcnt vmcnt(39)
; DI void post_phase(const P& p, int l, unsigned char* smem, int t0, int t1, int bstart, int bstride) {
;     ...
; #pragma unroll
;         for (int i = 0; i < 8; ++i) {
;             const int j = i * 256 + lane * 4;
;             const f32x4 hv = __builtin_nontemporal_load((const f32x4*)(h + j)), gt = *(const f32x4*)(md + 4096 + j), nw = *(const f32x4*)(p.norm_post + l * DM + j);
; #pragma unroll
;             for (int e = 0; e < 4; ++e) { y[i][e] = hv[e] + gt[e] * (y[i][e] * rstd * nw[e]); ss2 += y[i][e] * y[i][e]; }
;             __builtin_nontemporal_store(y[i], (f32x4*)(hdst + j));
;         }
	v_fma_f32 v88, v120, v212, v88
	v_fma_f32 v89, v121, v213, v89
	v_fma_f32 v90, v122, v214, v90
	v_fma_f32 v91, v123, v215, v91
	global_store_dwordx4 v0, v[88:91], s[16:17] offset:1024 sc1
	v_lshlrev_b32_e32 v212, 16, v56
	v_and_b32_e32 v213, 0xffff0000, v56
	v_lshlrev_b32_e32 v214, 16, v57
	v_and_b32_e32 v215, 0xffff0000, v57
	v_mul_f32_e32 v212, v13, v212
	v_mul_f32_e32 v213, v13, v213
	v_mul_f32_e32 v214, v13, v214
	v_mul_f32_e32 v215, v13, v215
	v_mul_f32_e32 v212, v28, v212
	v_mul_f32_e32 v213, v29, v213
	v_mul_f32_e32 v214, v30, v214
	v_mul_f32_e32 v215, v31, v215
	s_waitcnt vmcnt(39)
	v_fma_f32 v92, v124, v212, v92
	v_fma_f32 v93, v125, v213, v93
	v_fma_f32 v94, v126, v214, v94
	v_fma_f32 v95, v127, v215, v95
	global_store_dwordx4 v0, v[92:95], s[16:17] offset:2048 sc1
	v_lshlrev_b32_e32 v212, 16, v58
	v_and_b32_e32 v213, 0xffff0000, v58
	v_lshlrev_b32_e32 v214, 16, v59
	v_and_b32_e32 v215, 0xffff0000, v59
	v_mul_f32_e32 v212, v13, v212
	v_mul_f32_e32 v213, v13, v213
	v_mul_f32_e32 v214, v13, v214
	v_mul_f32_e32 v215, v13, v215
	v_mul_f32_e32 v212, v32, v212
	v_mul_f32_e32 v213, v33, v213
	v_mul_f32_e32 v214, v34, v214
	v_mul_f32_e32 v215, v35, v215
	s_waitcnt vmcnt(39)
	v_fma_f32 v96, v128, v212, v96
	v_fma_f32 v97, v129, v213, v97
	v_fma_f32 v98, v130, v214, v98
	v_fma_f32 v99, v131, v215, v99
	global_store_dwordx4 v0, v[96:99], s[16:17] offset:3072 sc1
	v_lshlrev_b32_e32 v212, 16, v60
	v_and_b32_e32 v213, 0xffff0000, v60
	v_lshlrev_b32_e32 v214, 16, v61
	v_and_b32_e32 v215, 0xffff0000, v61
	v_mul_f32_e32 v212, v13, v212
	v_mul_f32_e32 v213, v13, v213
	v_mul_f32_e32 v214, v13, v214
	v_mul_f32_e32 v215, v13, v215
	v_mul_f32_e32 v212, v36, v212
	v_mul_f32_e32 v213, v37, v213
	v_mul_f32_e32 v214, v38, v214
	v_mul_f32_e32 v215, v39, v215
	s_waitcnt vmcnt(39)
	v_fma_f32 v100, v132, v212, v100
	v_fma_f32 v101, v133, v213, v101
	v_fma_f32 v102, v134, v214, v102
	v_fma_f32 v103, v135, v215, v103
	global_store_dwordx4 v1, v[100:103], s[16:17] offset:0 sc1
	v_lshlrev_b32_e32 v212, 16, v62
	v_and_b32_e32 v213, 0xffff0000, v62
	v_lshlrev_b32_e32 v214, 16, v63
	v_and_b32_e32 v215, 0xffff0000, v63
	v_mul_f32_e32 v212, v13, v212
	v_mul_f32_e32 v213, v13, v213
	v_mul_f32_e32 v214, v13, v214
	v_mul_f32_e32 v215, v13, v215
	v_mul_f32_e32 v212, v40, v212
	v_mul_f32_e32 v213, v41, v213
	v_mul_f32_e32 v214, v42, v214
	v_mul_f32_e32 v215, v43, v215
	s_waitcnt vmcnt(39)
	v_fma_f32 v104, v136, v212, v104
	v_fma_f32 v105, v137, v213, v105
	v_fma_f32 v106, v138, v214, v106
	v_fma_f32 v107, v139, v215, v107
	global_store_dwordx4 v1, v[104:107], s[16:17] offset:1024 sc1
	v_lshlrev_b32_e32 v212, 16, v64
	v_and_b32_e32 v213, 0xffff0000, v64
	v_lshlrev_b32_e32 v214, 16, v65
	v_and_b32_e32 v215, 0xffff0000, v65
	v_mul_f32_e32 v212, v13, v212
	v_mul_f32_e32 v213, v13, v213
	v_mul_f32_e32 v214, v13, v214
	v_mul_f32_e32 v215, v13, v215
	v_mul_f32_e32 v212, v44, v212
	v_mul_f32_e32 v213, v45, v213
	v_mul_f32_e32 v214, v46, v214
	v_mul_f32_e32 v215, v47, v215
	s_waitcnt vmcnt(39)
	v_fma_f32 v108, v140, v212, v108
	v_fma_f32 v109, v141, v213, v109
	v_fma_f32 v110, v142, v214, v110
	v_fma_f32 v111, v143, v215, v111
	global_store_dwordx4 v1, v[108:111], s[16:17] offset:2048 sc1
	v_lshlrev_b32_e32 v212, 16, v66
	v_and_b32_e32 v213, 0xffff0000, v66
	v_lshlrev_b32_e32 v214, 16, v67
	v_and_b32_e32 v215, 0xffff0000, v67
	v_mul_f32_e32 v212, v13, v212
	v_mul_f32_e32 v213, v13, v213
	v_mul_f32_e32 v214, v13, v214
	v_mul_f32_e32 v215, v13, v215
	v_mul_f32_e32 v212, v48, v212
	v_mul_f32_e32 v213, v49, v213
	v_mul_f32_e32 v214, v50, v214
	v_mul_f32_e32 v215, v51, v215
	s_waitcnt vmcnt(39)
	v_fma_f32 v112, v144, v212, v112
	v_fma_f32 v113, v145, v213, v113
	v_fma_f32 v114, v146, v214, v114
	v_fma_f32 v115, v147, v215, v115
	global_store_dwordx4 v1, v[112:115], s[16:17] offset:3072 sc1
	global_load_dwordx4 v[84:87], v0, s[24:25] offset:0 nt
	global_load_dwordx4 v[88:91], v0, s[24:25] offset:1024 nt
	global_load_dwordx4 v[92:95], v0, s[24:25] offset:2048 nt
	global_load_dwordx4 v[96:99], v0, s[24:25] offset:3072 nt
	global_load_dwordx4 v[100:103], v1, s[24:25] offset:0 nt
	global_load_dwordx4 v[104:107], v1, s[24:25] offset:1024 nt
	global_load_dwordx4 v[108:111], v1, s[24:25] offset:2048 nt
	global_load_dwordx4 v[112:115], v1, s[24:25] offset:3072 nt
	v_lshlrev_b32_e32 v212, 16, v68
	v_and_b32_e32 v213, 0xffff0000, v68
	v_lshlrev_b32_e32 v214, 16, v69
	v_and_b32_e32 v215, 0xffff0000, v69
	v_mul_f32_e32 v212, v14, v212
	v_mul_f32_e32 v213, v14, v213
	v_mul_f32_e32 v214, v14, v214
	v_mul_f32_e32 v215, v14, v215
	v_mul_f32_e32 v212, v20, v212
	v_mul_f32_e32 v213, v21, v213
	v_mul_f32_e32 v214, v22, v214
	v_mul_f32_e32 v215, v23, v215
	s_waitcnt vmcnt(47)
	v_fma_f32 v148, v116, v212, v148
	v_fma_f32 v149, v117, v213, v149
	v_fma_f32 v150, v118, v214, v150
	v_fma_f32 v151, v119, v215, v151
	global_store_dwordx4 v0, v[148:151], s[18:19] offset:0 sc1
	v_lshlrev_b32_e32 v212, 16, v70
	v_and_b32_e32 v213, 0xffff0000, v70
	v_lshlrev_b32_e32 v214, 16, v71
	v_and_b32_e32 v215, 0xffff0000, v71
	v_mul_f32_e32 v212, v14, v212
	v_mul_f32_e32 v213, v14, v213
	v_mul_f32_e32 v214, v14, v214
	v_mul_f32_e32 v215, v14, v215
	v_mul_f32_e32 v212, v24, v212
	v_mul_f32_e32 v213, v25, v213
	v_mul_f32_e32 v214, v26, v214
	v_mul_f32_e32 v215, v27, v215
	s_waitcnt vmcnt(47)
	v_fma_f32 v152, v120, v212, v152
	v_fma_f32 v153, v121, v213, v153
	v_fma_f32 v154, v122, v214, v154
	v_fma_f32 v155, v123, v215, v155
	global_store_dwordx4 v0, v[152:155], s[18:19] offset:1024 sc1
	v_lshlrev_b32_e32 v212, 16, v72
	v_and_b32_e32 v213, 0xffff0000, v72
	v_lshlrev_b32_e32 v214, 16, v73
	v_and_b32_e32 v215, 0xffff0000, v73
	v_mul_f32_e32 v212, v14, v212
	v_mul_f32_e32 v213, v14, v213
	v_mul_f32_e32 v214, v14, v214
	v_mul_f32_e32 v215, v14, v215
	v_mul_f32_e32 v212, v28, v212
	v_mul_f32_e32 v213, v29, v213
	v_mul_f32_e32 v214, v30, v214
	v_mul_f32_e32 v215, v31, v215
	s_waitcnt vmcnt(47)
; DI float lo16(unsigned u) { return __uint_as_float(u << 16); }
; DI float hi16(unsigned u) { return __uint_as_float(u & 0xFFFF0000u); }
; DI void post_phase(const P& p, int l, unsigned char* smem, int t0, int t1, int bstart, int bstride) {
;     ...
;         f32x4 y[8]; float ss = 0.f;
; #pragma unroll
;         for (int i = 0; i < 8; ++i) {
;             const u32x2 w = __builtin_nontemporal_load((const u32x2*)(yo + (size_t)row * DM + i * 256 + lane * 4));
;             y[i] = (f32x4){lo16(w.x), hi16(w.x), lo16(w.y), hi16(w.y)};
;             ss += y[i][0] * y[i][0] + y[i][1] * y[i][1] + y[i][2] * y[i][2] + y[i][3] * y[i][3];
;         }
;         ss = wave_sum(ss);
;         const float rstd = rsqrtf(ss * (1.f / 2048.f) + 1e-6f);
;         const float* md = mod + (size_t)(l * 5 + mr) * 6144;
;         float ss2 = 0.f;
; #pragma unroll
;         for (int i = 0; i < 8; ++i) {
;             const int j = i * 256 + lane * 4;
;             const f32x4 hv = __builtin_nontemporal_load((const f32x4*)(h + j)), gt = *(const f32x4*)(md + 4096 + j), nw = *(const f32x4*)(p.norm_post + l * DM + j);
; #pragma unroll
;             for (int e = 0; e < 4; ++e) { y[i][e] = hv[e] + gt[e] * (y[i][e] * rstd * nw[e]); ss2 += y[i][e] * y[i][e]; }
;             __builtin_nontemporal_store(y[i], (f32x4*)(hdst + j));
;         }
	v_fma_f32 v156, v124, v212, v156
	v_fma_f32 v157, v125, v213, v157
	v_fma_f32 v158, v126, v214, v158
	v_fma_f32 v159, v127, v215, v159
	global_store_dwordx4 v0, v[156:159], s[18:19] offset:2048 sc1
	v_lshlrev_b32_e32 v212, 16, v74
	v_and_b32_e32 v213, 0xffff0000, v74
	v_lshlrev_b32_e32 v214, 16, v75
	v_and_b32_e32 v215, 0xffff0000, v75
	v_mul_f32_e32 v212, v14, v212
	v_mul_f32_e32 v213, v14, v213
	v_mul_f32_e32 v214, v14, v214
	v_mul_f32_e32 v215, v14, v215
	v_mul_f32_e32 v212, v32, v212
	v_mul_f32_e32 v213, v33, v213
	v_mul_f32_e32 v214, v34, v214
	v_mul_f32_e32 v215, v35, v215
	s_waitcnt vmcnt(47)
	v_fma_f32 v160, v128, v212, v160
	v_fma_f32 v161, v129, v213, v161
	v_fma_f32 v162, v130, v214, v162
	v_fma_f32 v163, v131, v215, v163
	global_store_dwordx4 v0, v[160:163], s[18:19] offset:3072 sc1
	v_lshlrev_b32_e32 v212, 16, v76
	v_and_b32_e32 v213, 0xffff0000, v76
	v_lshlrev_b32_e32 v214, 16, v77
	v_and_b32_e32 v215, 0xffff0000, v77
	v_mul_f32_e32 v212, v14, v212
	v_mul_f32_e32 v213, v14, v213
	v_mul_f32_e32 v214, v14, v214
	v_mul_f32_e32 v215, v14, v215
	v_mul_f32_e32 v212, v36, v212
	v_mul_f32_e32 v213, v37, v213
	v_mul_f32_e32 v214, v38, v214
	v_mul_f32_e32 v215, v39, v215
	s_waitcnt vmcnt(47)
	v_fma_f32 v164, v132, v212, v164
	v_fma_f32 v165, v133, v213, v165
	v_fma_f32 v166, v134, v214, v166
	v_fma_f32 v167, v135, v215, v167
	global_store_dwordx4 v1, v[164:167], s[18:19] offset:0 sc1
	v_lshlrev_b32_e32 v212, 16, v78
	v_and_b32_e32 v213, 0xffff0000, v78
	v_lshlrev_b32_e32 v214, 16, v79
	v_and_b32_e32 v215, 0xffff0000, v79
	v_mul_f32_e32 v212, v14, v212
	v_mul_f32_e32 v213, v14, v213
	v_mul_f32_e32 v214, v14, v214
	v_mul_f32_e32 v215, v14, v215
	v_mul_f32_e32 v212, v40, v212
	v_mul_f32_e32 v213, v41, v213
	v_mul_f32_e32 v214, v42, v214
	v_mul_f32_e32 v215, v43, v215
	s_waitcnt vmcnt(47)
	v_fma_f32 v168, v136, v212, v168
	v_fma_f32 v169, v137, v213, v169
	v_fma_f32 v170, v138, v214, v170
	v_fma_f32 v171, v139, v215, v171
	global_store_dwordx4 v1, v[168:171], s[18:19] offset:1024 sc1
	v_lshlrev_b32_e32 v212, 16, v80
	v_and_b32_e32 v213, 0xffff0000, v80
	v_lshlrev_b32_e32 v214, 16, v81
	v_and_b32_e32 v215, 0xffff0000, v81
	v_mul_f32_e32 v212, v14, v212
	v_mul_f32_e32 v213, v14, v213
	v_mul_f32_e32 v214, v14, v214
	v_mul_f32_e32 v215, v14, v215
	v_mul_f32_e32 v212, v44, v212
	v_mul_f32_e32 v213, v45, v213
	v_mul_f32_e32 v214, v46, v214
	v_mul_f32_e32 v215, v47, v215
	s_waitcnt vmcnt(47)
	v_fma_f32 v172, v140, v212, v172
	v_fma_f32 v173, v141, v213, v173
	v_fma_f32 v174, v142, v214, v174
	v_fma_f32 v175, v143, v215, v175
	global_store_dwordx4 v1, v[172:175], s[18:19] offset:2048 sc1
	v_lshlrev_b32_e32 v212, 16, v82
	v_and_b32_e32 v213, 0xffff0000, v82
	v_lshlrev_b32_e32 v214, 16, v83
	v_and_b32_e32 v215, 0xffff0000, v83
	v_mul_f32_e32 v212, v14, v212
	v_mul_f32_e32 v213, v14, v213
	v_mul_f32_e32 v214, v14, v214
	v_mul_f32_e32 v215, v14, v215
	v_mul_f32_e32 v212, v48, v212
	v_mul_f32_e32 v213, v49, v213
	v_mul_f32_e32 v214, v50, v214
	v_mul_f32_e32 v215, v51, v215
	s_waitcnt vmcnt(47)
	v_fma_f32 v176, v144, v212, v176
	v_fma_f32 v177, v145, v213, v177
	v_fma_f32 v178, v146, v214, v178
	v_fma_f32 v179, v147, v215, v179
	global_store_dwordx4 v1, v[176:179], s[18:19] offset:3072 sc1
	global_load_dwordx4 v[148:151], v0, s[26:27] offset:0 nt
	global_load_dwordx4 v[152:155], v0, s[26:27] offset:1024 nt
	global_load_dwordx4 v[156:159], v0, s[26:27] offset:2048 nt
	global_load_dwordx4 v[160:163], v0, s[26:27] offset:3072 nt
	global_load_dwordx4 v[164:167], v1, s[26:27] offset:0 nt
	global_load_dwordx4 v[168:171], v1, s[26:27] offset:1024 nt
	global_load_dwordx4 v[172:175], v1, s[26:27] offset:2048 nt
	global_load_dwordx4 v[176:179], v1, s[26:27] offset:3072 nt
	s_waitcnt vmcnt(40)
	v_lshlrev_b32_e32 v212, 16, v180
	v_and_b32_e32 v213, 0xffff0000, v180
	v_lshlrev_b32_e32 v214, 16, v181
	v_and_b32_e32 v215, 0xffff0000, v181
	v_mul_f32_e32 v9, v212, v212
	v_mul_f32_e32 v15, v213, v213
	v_fmac_f32_e32 v9, v214, v214
	v_fmac_f32_e32 v15, v215, v215
	v_lshlrev_b32_e32 v212, 16, v182
	v_and_b32_e32 v213, 0xffff0000, v182
	v_lshlrev_b32_e32 v214, 16, v183
	v_and_b32_e32 v215, 0xffff0000, v183
	v_fmac_f32_e32 v9, v212, v212
	v_fmac_f32_e32 v15, v213, v213
	v_fmac_f32_e32 v9, v214, v214
	v_fmac_f32_e32 v15, v215, v215
	v_lshlrev_b32_e32 v212, 16, v184
	v_and_b32_e32 v213, 0xffff0000, v184
	v_lshlrev_b32_e32 v214, 16, v185
	v_and_b32_e32 v215, 0xffff0000, v185
	v_fmac_f32_e32 v9, v212, v212
	v_fmac_f32_e32 v15, v213, v213
	v_fmac_f32_e32 v9, v214, v214
	v_fmac_f32_e32 v15, v215, v215
	v_lshlrev_b32_e32 v212, 16, v186
	v_and_b32_e32 v213, 0xffff0000, v186
	v_lshlrev_b32_e32 v214, 16, v187
	v_and_b32_e32 v215, 0xffff0000, v187
	v_fmac_f32_e32 v9, v212, v212
	v_fmac_f32_e32 v15, v213, v213
	v_fmac_f32_e32 v9, v214, v214
	v_fmac_f32_e32 v15, v215, v215
	v_lshlrev_b32_e32 v212, 16, v188
	v_and_b32_e32 v213, 0xffff0000, v188
	v_lshlrev_b32_e32 v214, 16, v189
	v_and_b32_e32 v215, 0xffff0000, v189
	v_fmac_f32_e32 v9, v212, v212
	v_fmac_f32_e32 v15, v213, v213
	v_fmac_f32_e32 v9, v214, v214
	v_fmac_f32_e32 v15, v215, v215
	v_lshlrev_b32_e32 v212, 16, v190
	v_and_b32_e32 v213, 0xffff0000, v190
	v_lshlrev_b32_e32 v214, 16, v191
	v_and_b32_e32 v215, 0xffff0000, v191
	v_fmac_f32_e32 v9, v212, v212
	v_fmac_f32_e32 v15, v213, v213
	v_fmac_f32_e32 v9, v214, v214
	v_fmac_f32_e32 v15, v215, v215
	v_lshlrev_b32_e32 v212, 16, v192
	v_and_b32_e32 v213, 0xffff0000, v192
	v_lshlrev_b32_e32 v214, 16, v193
	v_and_b32_e32 v215, 0xffff0000, v193
	v_fmac_f32_e32 v9, v212, v212
	v_fmac_f32_e32 v15, v213, v213
	v_fmac_f32_e32 v9, v214, v214
	v_fmac_f32_e32 v15, v215, v215
; DI float lo16(unsigned u) { return __uint_as_float(u << 16); }
; DI float hi16(unsigned u) { return __uint_as_float(u & 0xFFFF0000u); }
; DI void post_phase(const P& p, int l, unsigned char* smem, int t0, int t1, int bstart, int bstride) {
;     ...
;         f32x4 y[8]; float ss = 0.f;
; #pragma unroll
;         for (int i = 0; i < 8; ++i) {
;             const u32x2 w = __builtin_nontemporal_load((const u32x2*)(yo + (size_t)row * DM + i * 256 + lane * 4));
;             y[i] = (f32x4){lo16(w.x), hi16(w.x), lo16(w.y), hi16(w.y)};
;             ss += y[i][0] * y[i][0] + y[i][1] * y[i][1] + y[i][2] * y[i][2] + y[i][3] * y[i][3];
;         }
;         ss = wave_sum(ss);
;         const float rstd = rsqrtf(ss * (1.f / 2048.f) + 1e-6f);
;         const float* md = mod + (size_t)(l * 5 + mr) * 6144;
;         float ss2 = 0.f;
; #pragma unroll
;         for (int i = 0; i < 8; ++i) {
;             const int j = i * 256 + lane * 4;
;             const f32x4 hv = __builtin_nontemporal_load((const f32x4*)(h + j)), gt = *(const f32x4*)(md + 4096 + j), nw = *(const f32x4*)(p.norm_post + l * DM + j);
; #pragma unroll
;             for (int e = 0; e < 4; ++e) { y[i][e] = hv[e] + gt[e] * (y[i][e] * rstd * nw[e]); ss2 += y[i][e] * y[i][e]; }
;             __builtin_nontemporal_store(y[i], (f32x4*)(hdst + j));
;         }
	v_lshlrev_b32_e32 v212, 16, v194
	v_and_b32_e32 v213, 0xffff0000, v194
	v_lshlrev_b32_e32 v214, 16, v195
	v_and_b32_e32 v215, 0xffff0000, v195
	v_fmac_f32_e32 v9, v212, v212
	v_fmac_f32_e32 v15, v213, v213
	v_fmac_f32_e32 v9, v214, v214
	v_fmac_f32_e32 v15, v215, v215
	v_add_f32_e32 v9, v9, v15
	v_lshlrev_b32_e32 v212, 16, v196
	v_and_b32_e32 v213, 0xffff0000, v196
	v_lshlrev_b32_e32 v214, 16, v197
	v_and_b32_e32 v215, 0xffff0000, v197
	v_mul_f32_e32 v10, v212, v212
	v_mul_f32_e32 v16, v213, v213
	v_fmac_f32_e32 v10, v214, v214
	v_fmac_f32_e32 v16, v215, v215
	v_lshlrev_b32_e32 v212, 16, v198
	v_and_b32_e32 v213, 0xffff0000, v198
	v_lshlrev_b32_e32 v214, 16, v199
	v_and_b32_e32 v215, 0xffff0000, v199
	v_fmac_f32_e32 v10, v212, v212
	v_fmac_f32_e32 v16, v213, v213
	v_fmac_f32_e32 v10, v214, v214
	v_fmac_f32_e32 v16, v215, v215
	v_lshlrev_b32_e32 v212, 16, v200
	v_and_b32_e32 v213, 0xffff0000, v200
	v_lshlrev_b32_e32 v214, 16, v201
	v_and_b32_e32 v215, 0xffff0000, v201
	v_fmac_f32_e32 v10, v212, v212
	v_fmac_f32_e32 v16, v213, v213
	v_fmac_f32_e32 v10, v214, v214
	v_fmac_f32_e32 v16, v215, v215
	v_lshlrev_b32_e32 v212, 16, v202
	v_and_b32_e32 v213, 0xffff0000, v202
	v_lshlrev_b32_e32 v214, 16, v203
	v_and_b32_e32 v215, 0xffff0000, v203
	v_fmac_f32_e32 v10, v212, v212
	v_fmac_f32_e32 v16, v213, v213
	v_fmac_f32_e32 v10, v214, v214
	v_fmac_f32_e32 v16, v215, v215
	v_lshlrev_b32_e32 v212, 16, v204
	v_and_b32_e32 v213, 0xffff0000, v204
	v_lshlrev_b32_e32 v214, 16, v205
	v_and_b32_e32 v215, 0xffff0000, v205
	v_fmac_f32_e32 v10, v212, v212
	v_fmac_f32_e32 v16, v213, v213
	v_fmac_f32_e32 v10, v214, v214
	v_fmac_f32_e32 v16, v215, v215
	v_lshlrev_b32_e32 v212, 16, v206
	v_and_b32_e32 v213, 0xffff0000, v206
	v_lshlrev_b32_e32 v214, 16, v207
	v_and_b32_e32 v215, 0xffff0000, v207
	v_fmac_f32_e32 v10, v212, v212
	v_fmac_f32_e32 v16, v213, v213
	v_fmac_f32_e32 v10, v214, v214
	v_fmac_f32_e32 v16, v215, v215
	v_lshlrev_b32_e32 v212, 16, v208
	v_and_b32_e32 v213, 0xffff0000, v208
	v_lshlrev_b32_e32 v214, 16, v209
	v_and_b32_e32 v215, 0xffff0000, v209
	v_fmac_f32_e32 v10, v212, v212
	v_fmac_f32_e32 v16, v213, v213
	v_fmac_f32_e32 v10, v214, v214
	v_fmac_f32_e32 v16, v215, v215
	v_lshlrev_b32_e32 v212, 16, v210
	v_and_b32_e32 v213, 0xffff0000, v210
	v_lshlrev_b32_e32 v214, 16, v211
	v_and_b32_e32 v215, 0xffff0000, v211
	v_fmac_f32_e32 v10, v212, v212
	v_fmac_f32_e32 v16, v213, v213
	v_fmac_f32_e32 v10, v214, v214
	v_fmac_f32_e32 v16, v215, v215
	v_add_f32_e32 v10, v10, v16
	ds_bpermute_b32 v11, v3, v9
	ds_bpermute_b32 v12, v3, v10
	s_waitcnt lgkmcnt(1)
	v_add_f32_e32 v9, v9, v11
	s_waitcnt lgkmcnt(0)
	v_add_f32_e32 v10, v10, v12
	ds_bpermute_b32 v11, v4, v9
	ds_bpermute_b32 v12, v4, v10
	s_waitcnt lgkmcnt(1)
	v_add_f32_e32 v9, v9, v11
	s_waitcnt lgkmcnt(0)
	v_add_f32_e32 v10, v10, v12
	ds_bpermute_b32 v11, v5, v9
	ds_bpermute_b32 v12, v5, v10
	s_waitcnt lgkmcnt(1)
	v_add_f32_e32 v9, v9, v11
	s_waitcnt lgkmcnt(0)
	v_add_f32_e32 v10, v10, v12
	ds_bpermute_b32 v11, v6, v9
	ds_bpermute_b32 v12, v6, v10
	s_waitcnt lgkmcnt(1)
	v_add_f32_e32 v9, v9, v11
	s_waitcnt lgkmcnt(0)
	v_add_f32_e32 v10, v10, v12
	ds_bpermute_b32 v11, v7, v9
	ds_bpermute_b32 v12, v7, v10
	s_waitcnt lgkmcnt(1)
	v_add_f32_e32 v9, v9, v11
	s_waitcnt lgkmcnt(0)
	v_add_f32_e32 v10, v10, v12
	ds_bpermute_b32 v11, v8, v9
	ds_bpermute_b32 v12, v8, v10
	s_waitcnt lgkmcnt(1)
	v_add_f32_e32 v9, v9, v11
	s_waitcnt lgkmcnt(0)
	v_add_f32_e32 v10, v10, v12
	v_mov_b32_e32 v11, 0x358637bd
	v_fmamk_f32 v9, v9, 0x3a000000, v11
	v_fmamk_f32 v10, v10, 0x3a000000, v11
	v_rsq_f32_e32 v13, v9
	v_rsq_f32_e32 v14, v10
	s_nop 0
	v_lshlrev_b32_e32 v212, 16, v180
	v_and_b32_e32 v213, 0xffff0000, v180
	v_lshlrev_b32_e32 v214, 16, v181
	v_and_b32_e32 v215, 0xffff0000, v181
	v_mul_f32_e32 v212, v13, v212
	v_mul_f32_e32 v213, v13, v213
	v_mul_f32_e32 v214, v13, v214
	v_mul_f32_e32 v215, v13, v215
	v_mul_f32_e32 v212, v20, v212
	v_mul_f32_e32 v213, v21, v213
	v_mul_f32_e32 v214, v22, v214
	v_mul_f32_e32 v215, v23, v215
	s_waitcnt vmcnt(23)
	v_fma_f32 v84, v216, v212, v84
	v_fma_f32 v85, v217, v213, v85
	v_fma_f32 v86, v218, v214, v86
	v_fma_f32 v87, v219, v215, v87
	global_store_dwordx4 v0, v[84:87], s[24:25] offset:0 sc1
	v_lshlrev_b32_e32 v212, 16, v182
	v_and_b32_e32 v213, 0xffff0000, v182
	v_lshlrev_b32_e32 v214, 16, v183
	v_and_b32_e32 v215, 0xffff0000, v183
	v_mul_f32_e32 v212, v13, v212
	v_mul_f32_e32 v213, v13, v213
	v_mul_f32_e32 v214, v13, v214
	v_mul_f32_e32 v215, v13, v215
	v_mul_f32_e32 v212, v24, v212
	v_mul_f32_e32 v213, v25, v213
	v_mul_f32_e32 v214, v26, v214
	v_mul_f32_e32 v215, v27, v215
	s_waitcnt vmcnt(23)
	v_fma_f32 v88, v220, v212, v88
	v_fma_f32 v89, v221, v213, v89
	v_fma_f32 v90, v222, v214, v90
	v_fma_f32 v91, v223, v215, v91
	global_store_dwordx4 v0, v[88:91], s[24:25] offset:1024 sc1
	v_lshlrev_b32_e32 v212, 16, v184
	v_and_b32_e32 v213, 0xffff0000, v184
	v_lshlrev_b32_e32 v214, 16, v185
	v_and_b32_e32 v215, 0xffff0000, v185
	v_mul_f32_e32 v212, v13, v212
	v_mul_f32_e32 v213, v13, v213
	v_mul_f32_e32 v214, v13, v214
	v_mul_f32_e32 v215, v13, v215
	v_mul_f32_e32 v212, v28, v212
	v_mul_f32_e32 v213, v29, v213
	v_mul_f32_e32 v214, v30, v214
	v_mul_f32_e32 v215, v31, v215
	s_waitcnt vmcnt(23)
	v_fma_f32 v92, v224, v212, v92
	v_fma_f32 v93, v225, v213, v93
	v_fma_f32 v94, v226, v214, v94
	v_fma_f32 v95, v227, v215, v95
	global_store_dwordx4 v0, v[92:95], s[24:25] offset:2048 sc1
	v_lshlrev_b32_e32 v212, 16, v186
	v_and_b32_e32 v213, 0xffff0000, v186
	v_lshlrev_b32_e32 v214, 16, v187
	v_and_b32_e32 v215, 0xffff0000, v187
	v_mul_f32_e32 v212, v13, v212
	v_mul_f32_e32 v213, v13, v213
	v_mul_f32_e32 v214, v13, v214
	v_mul_f32_e32 v215, v13, v215
	v_mul_f32_e32 v212, v32, v212
	v_mul_f32_e32 v213, v33, v213
	v_mul_f32_e32 v214, v34, v214
	v_mul_f32_e32 v215, v35, v215
	s_waitcnt vmcnt(23)
; DI void post_phase(const P& p, int l, unsigned char* smem, int t0, int t1, int bstart, int bstride) {
;     ...
; #pragma unroll
;         for (int i = 0; i < 8; ++i) {
;             const int j = i * 256 + lane * 4;
;             const f32x4 hv = __builtin_nontemporal_load((const f32x4*)(h + j)), gt = *(const f32x4*)(md + 4096 + j), nw = *(const f32x4*)(p.norm_post + l * DM + j);
; #pragma unroll
;             for (int e = 0; e < 4; ++e) { y[i][e] = hv[e] + gt[e] * (y[i][e] * rstd * nw[e]); ss2 += y[i][e] * y[i][e]; }
;             __builtin_nontemporal_store(y[i], (f32x4*)(hdst + j));
;         }
	v_fma_f32 v96, v228, v212, v96
	v_fma_f32 v97, v229, v213, v97
	v_fma_f32 v98, v230, v214, v98
	v_fma_f32 v99, v231, v215, v99
	global_store_dwordx4 v0, v[96:99], s[24:25] offset:3072 sc1
	v_lshlrev_b32_e32 v212, 16, v188
	v_and_b32_e32 v213, 0xffff0000, v188
	v_lshlrev_b32_e32 v214, 16, v189
	v_and_b32_e32 v215, 0xffff0000, v189
	v_mul_f32_e32 v212, v13, v212
	v_mul_f32_e32 v213, v13, v213
	v_mul_f32_e32 v214, v13, v214
	v_mul_f32_e32 v215, v13, v215
	v_mul_f32_e32 v212, v36, v212
	v_mul_f32_e32 v213, v37, v213
	v_mul_f32_e32 v214, v38, v214
	v_mul_f32_e32 v215, v39, v215
	s_waitcnt vmcnt(23)
	v_fma_f32 v100, v232, v212, v100
	v_fma_f32 v101, v233, v213, v101
	v_fma_f32 v102, v234, v214, v102
	v_fma_f32 v103, v235, v215, v103
	global_store_dwordx4 v1, v[100:103], s[24:25] offset:0 sc1
	v_lshlrev_b32_e32 v212, 16, v190
	v_and_b32_e32 v213, 0xffff0000, v190
	v_lshlrev_b32_e32 v214, 16, v191
	v_and_b32_e32 v215, 0xffff0000, v191
	v_mul_f32_e32 v212, v13, v212
	v_mul_f32_e32 v213, v13, v213
	v_mul_f32_e32 v214, v13, v214
	v_mul_f32_e32 v215, v13, v215
	v_mul_f32_e32 v212, v40, v212
	v_mul_f32_e32 v213, v41, v213
	v_mul_f32_e32 v214, v42, v214
	v_mul_f32_e32 v215, v43, v215
	s_waitcnt vmcnt(23)
	v_fma_f32 v104, v236, v212, v104
	v_fma_f32 v105, v237, v213, v105
	v_fma_f32 v106, v238, v214, v106
	v_fma_f32 v107, v239, v215, v107
	global_store_dwordx4 v1, v[104:107], s[24:25] offset:1024 sc1
	v_lshlrev_b32_e32 v212, 16, v192
	v_and_b32_e32 v213, 0xffff0000, v192
	v_lshlrev_b32_e32 v214, 16, v193
	v_and_b32_e32 v215, 0xffff0000, v193
	v_mul_f32_e32 v212, v13, v212
	v_mul_f32_e32 v213, v13, v213
	v_mul_f32_e32 v214, v13, v214
	v_mul_f32_e32 v215, v13, v215
	v_mul_f32_e32 v212, v44, v212
	v_mul_f32_e32 v213, v45, v213
	v_mul_f32_e32 v214, v46, v214
	v_mul_f32_e32 v215, v47, v215
	s_waitcnt vmcnt(23)
	v_fma_f32 v108, v240, v212, v108
	v_fma_f32 v109, v241, v213, v109
	v_fma_f32 v110, v242, v214, v110
	v_fma_f32 v111, v243, v215, v111
	global_store_dwordx4 v1, v[108:111], s[24:25] offset:2048 sc1
	v_lshlrev_b32_e32 v212, 16, v194
	v_and_b32_e32 v213, 0xffff0000, v194
	v_lshlrev_b32_e32 v214, 16, v195
	v_and_b32_e32 v215, 0xffff0000, v195
	v_mul_f32_e32 v212, v13, v212
	v_mul_f32_e32 v213, v13, v213
	v_mul_f32_e32 v214, v13, v214
	v_mul_f32_e32 v215, v13, v215
	v_mul_f32_e32 v212, v48, v212
	v_mul_f32_e32 v213, v49, v213
	v_mul_f32_e32 v214, v50, v214
	v_mul_f32_e32 v215, v51, v215
	s_waitcnt vmcnt(23)
	v_fma_f32 v112, v244, v212, v112
	v_fma_f32 v113, v245, v213, v113
	v_fma_f32 v114, v246, v214, v114
	v_fma_f32 v115, v247, v215, v115
	global_store_dwordx4 v1, v[112:115], s[24:25] offset:3072 sc1
	v_lshlrev_b32_e32 v212, 16, v196
	v_and_b32_e32 v213, 0xffff0000, v196
	v_lshlrev_b32_e32 v214, 16, v197
	v_and_b32_e32 v215, 0xffff0000, v197
	v_mul_f32_e32 v212, v14, v212
	v_mul_f32_e32 v213, v14, v213
	v_mul_f32_e32 v214, v14, v214
	v_mul_f32_e32 v215, v14, v215
	v_mul_f32_e32 v212, v20, v212
	v_mul_f32_e32 v213, v21, v213
	v_mul_f32_e32 v214, v22, v214
	v_mul_f32_e32 v215, v23, v215
	s_waitcnt vmcnt(15)
	v_fma_f32 v148, v216, v212, v148
	v_fma_f32 v149, v217, v213, v149
	v_fma_f32 v150, v218, v214, v150
	v_fma_f32 v151, v219, v215, v151
	global_store_dwordx4 v0, v[148:151], s[26:27] offset:0 sc1
	v_lshlrev_b32_e32 v212, 16, v198
	v_and_b32_e32 v213, 0xffff0000, v198
	v_lshlrev_b32_e32 v214, 16, v199
	v_and_b32_e32 v215, 0xffff0000, v199
	v_mul_f32_e32 v212, v14, v212
	v_mul_f32_e32 v213, v14, v213
	v_mul_f32_e32 v214, v14, v214
	v_mul_f32_e32 v215, v14, v215
	v_mul_f32_e32 v212, v24, v212
	v_mul_f32_e32 v213, v25, v213
	v_mul_f32_e32 v214, v26, v214
	v_mul_f32_e32 v215, v27, v215
	s_waitcnt vmcnt(15)
	v_fma_f32 v152, v220, v212, v152
	v_fma_f32 v153, v221, v213, v153
	v_fma_f32 v154, v222, v214, v154
	v_fma_f32 v155, v223, v215, v155
	global_store_dwordx4 v0, v[152:155], s[26:27] offset:1024 sc1
	v_lshlrev_b32_e32 v212, 16, v200
	v_and_b32_e32 v213, 0xffff0000, v200
	v_lshlrev_b32_e32 v214, 16, v201
	v_and_b32_e32 v215, 0xffff0000, v201
	v_mul_f32_e32 v212, v14, v212
	v_mul_f32_e32 v213, v14, v213
	v_mul_f32_e32 v214, v14, v214
	v_mul_f32_e32 v215, v14, v215
	v_mul_f32_e32 v212, v28, v212
	v_mul_f32_e32 v213, v29, v213
	v_mul_f32_e32 v214, v30, v214
	v_mul_f32_e32 v215, v31, v215
	s_waitcnt vmcnt(15)
	v_fma_f32 v156, v224, v212, v156
	v_fma_f32 v157, v225, v213, v157
	v_fma_f32 v158, v226, v214, v158
	v_fma_f32 v159, v227, v215, v159
	global_store_dwordx4 v0, v[156:159], s[26:27] offset:2048 sc1
	v_lshlrev_b32_e32 v212, 16, v202
	v_and_b32_e32 v213, 0xffff0000, v202
	v_lshlrev_b32_e32 v214, 16, v203
	v_and_b32_e32 v215, 0xffff0000, v203
	v_mul_f32_e32 v212, v14, v212
	v_mul_f32_e32 v213, v14, v213
	v_mul_f32_e32 v214, v14, v214
	v_mul_f32_e32 v215, v14, v215
	v_mul_f32_e32 v212, v32, v212
	v_mul_f32_e32 v213, v33, v213
	v_mul_f32_e32 v214, v34, v214
	v_mul_f32_e32 v215, v35, v215
	s_waitcnt vmcnt(15)
	v_fma_f32 v160, v228, v212, v160
	v_fma_f32 v161, v229, v213, v161
	v_fma_f32 v162, v230, v214, v162
	v_fma_f32 v163, v231, v215, v163
	global_store_dwordx4 v0, v[160:163], s[26:27] offset:3072 sc1
	v_lshlrev_b32_e32 v212, 16, v204
	v_and_b32_e32 v213, 0xffff0000, v204
	v_lshlrev_b32_e32 v214, 16, v205
	v_and_b32_e32 v215, 0xffff0000, v205
	v_mul_f32_e32 v212, v14, v212
	v_mul_f32_e32 v213, v14, v213
	v_mul_f32_e32 v214, v14, v214
	v_mul_f32_e32 v215, v14, v215
	v_mul_f32_e32 v212, v36, v212
	v_mul_f32_e32 v213, v37, v213
	v_mul_f32_e32 v214, v38, v214
	v_mul_f32_e32 v215, v39, v215
	s_waitcnt vmcnt(15)
; DI float lo16(unsigned u) { return __uint_as_float(u << 16); }
; DI float hi16(unsigned u) { return __uint_as_float(u & 0xFFFF0000u); }
; DI int osgpr(int v) { asm volatile("" : "+s"(v)); return v; }
; DI void post_phase(const P& p, int l, unsigned char* smem, int t0, int t1, int bstart, int bstride) {
;     ...
;     for (int rt = t0 + osgpr(bstart); rt < t1; rt += bstride) {
;       for (int rr = 0; rr < 2; ++rr) {
;         const int row = rt * 16 + wave * 2 + rr;
;         const int mr = row < NLAT ? (row >> 11) : 4;
;         const float* h = l == 0 ? (row < NLAT ? p.x + (size_t)row * DM : p.ctx + (size_t)(row - NLAT) * DM) : p.out + (size_t)row * DM;
;         float* hdst = row < NLAT ? p.out + (size_t)row * DM : hc + (size_t)(row - NLAT) * DM;
;         f32x4 y[8]; float ss = 0.f;
; #pragma unroll
;         for (int i = 0; i < 8; ++i) {
;             const u32x2 w = __builtin_nontemporal_load((const u32x2*)(yo + (size_t)row * DM + i * 256 + lane * 4));
;             y[i] = (f32x4){lo16(w.x), hi16(w.x), lo16(w.y), hi16(w.y)};
;             ss += y[i][0] * y[i][0] + y[i][1] * y[i][1] + y[i][2] * y[i][2] + y[i][3] * y[i][3];
;         }
;         ss = wave_sum(ss);
;         const float rstd = rsqrtf(ss * (1.f / 2048.f) + 1e-6f);
;         const float* md = mod + (size_t)(l * 5 + mr) * 6144;
;         float ss2 = 0.f;
; #pragma unroll
;         for (int i = 0; i < 8; ++i) {
;             const int j = i * 256 + lane * 4;
;             const f32x4 hv = __builtin_nontemporal_load((const f32x4*)(h + j)), gt = *(const f32x4*)(md + 4096 + j), nw = *(const f32x4*)(p.norm_post + l * DM + j);
; #pragma unroll
;             for (int e = 0; e < 4; ++e) { y[i][e] = hv[e] + gt[e] * (y[i][e] * rstd * nw[e]); ss2 += y[i][e] * y[i][e]; }
;             __builtin_nontemporal_store(y[i], (f32x4*)(hdst + j));
;         }
	v_fma_f32 v164, v232, v212, v164
	v_fma_f32 v165, v233, v213, v165
	v_fma_f32 v166, v234, v214, v166
	v_fma_f32 v167, v235, v215, v167
	global_store_dwordx4 v1, v[164:167], s[26:27] offset:0 sc1
	v_lshlrev_b32_e32 v212, 16, v206
	v_and_b32_e32 v213, 0xffff0000, v206
	v_lshlrev_b32_e32 v214, 16, v207
	v_and_b32_e32 v215, 0xffff0000, v207
	v_mul_f32_e32 v212, v14, v212
	v_mul_f32_e32 v213, v14, v213
	v_mul_f32_e32 v214, v14, v214
	v_mul_f32_e32 v215, v14, v215
	v_mul_f32_e32 v212, v40, v212
	v_mul_f32_e32 v213, v41, v213
	v_mul_f32_e32 v214, v42, v214
	v_mul_f32_e32 v215, v43, v215
	s_waitcnt vmcnt(15)
	v_fma_f32 v168, v236, v212, v168
	v_fma_f32 v169, v237, v213, v169
	v_fma_f32 v170, v238, v214, v170
	v_fma_f32 v171, v239, v215, v171
	global_store_dwordx4 v1, v[168:171], s[26:27] offset:1024 sc1
	v_lshlrev_b32_e32 v212, 16, v208
	v_and_b32_e32 v213, 0xffff0000, v208
	v_lshlrev_b32_e32 v214, 16, v209
	v_and_b32_e32 v215, 0xffff0000, v209
	v_mul_f32_e32 v212, v14, v212
	v_mul_f32_e32 v213, v14, v213
	v_mul_f32_e32 v214, v14, v214
	v_mul_f32_e32 v215, v14, v215
	v_mul_f32_e32 v212, v44, v212
	v_mul_f32_e32 v213, v45, v213
	v_mul_f32_e32 v214, v46, v214
	v_mul_f32_e32 v215, v47, v215
	s_waitcnt vmcnt(15)
	v_fma_f32 v172, v240, v212, v172
	v_fma_f32 v173, v241, v213, v173
	v_fma_f32 v174, v242, v214, v174
	v_fma_f32 v175, v243, v215, v175
	global_store_dwordx4 v1, v[172:175], s[26:27] offset:2048 sc1
	v_lshlrev_b32_e32 v212, 16, v210
	v_and_b32_e32 v213, 0xffff0000, v210
	v_lshlrev_b32_e32 v214, 16, v211
	v_and_b32_e32 v215, 0xffff0000, v211
	v_mul_f32_e32 v212, v14, v212
	v_mul_f32_e32 v213, v14, v213
	v_mul_f32_e32 v214, v14, v214
	v_mul_f32_e32 v215, v14, v215
	v_mul_f32_e32 v212, v48, v212
	v_mul_f32_e32 v213, v49, v213
	v_mul_f32_e32 v214, v50, v214
	v_mul_f32_e32 v215, v51, v215
	s_waitcnt vmcnt(15)
	v_fma_f32 v176, v244, v212, v176
	v_fma_f32 v177, v245, v213, v177
	v_fma_f32 v178, v246, v214, v178
	v_fma_f32 v179, v247, v215, v179
	global_store_dwordx4 v1, v[176:179], s[26:27] offset:3072 sc1
	s_add_u32 s2, s3, s10
	s_cmpk_lt_i32 s2, 0x200
	s_cbranch_scc1 .Lp1_pair
	s_branch .LBB0_805
.Lp1_single:
	s_lshl_b32 s12, s2, 4
	s_add_u32 s12, s12, s11
	s_lshl_b32 s14, s12, 12
	s_add_u32 s14, s14, 0x6c3c000
	s_add_u32 s14, s4, s14
	s_addc_u32 s15, s5, 0
	s_lshl_b32 s16, s12, 13
	s_add_u32 s16, s6, s16
	s_addc_u32 s17, s7, 0
	s_add_u32 s18, s16, 0x2000
	s_addc_u32 s19, s17, 0
	s_lshr_b32 s20, s12, 11
	s_add_u32 s20, s20, 5
	s_mul_i32 s20, s20, 0x6000
	s_add_u32 s20, s20, 0x4804000
	s_add_u32 s20, s4, s20
	s_addc_u32 s21, s5, 0
	global_load_dwordx2 v[52:53], v2, s[14:15] offset:0 nt
	global_load_dwordx2 v[54:55], v2, s[14:15] offset:512 nt
	global_load_dwordx2 v[56:57], v2, s[14:15] offset:1024 nt
	global_load_dwordx2 v[58:59], v2, s[14:15] offset:1536 nt
	global_load_dwordx2 v[60:61], v2, s[14:15] offset:2048 nt
	global_load_dwordx2 v[62:63], v2, s[14:15] offset:2560 nt
	global_load_dwordx2 v[64:65], v2, s[14:15] offset:3072 nt
	global_load_dwordx2 v[66:67], v2, s[14:15] offset:3584 nt
	global_load_dwordx2 v[68:69], v17, s[14:15] offset:0 nt
	global_load_dwordx2 v[70:71], v17, s[14:15] offset:512 nt
	global_load_dwordx2 v[72:73], v17, s[14:15] offset:1024 nt
	global_load_dwordx2 v[74:75], v17, s[14:15] offset:1536 nt
	global_load_dwordx2 v[76:77], v17, s[14:15] offset:2048 nt
	global_load_dwordx2 v[78:79], v17, s[14:15] offset:2560 nt
	global_load_dwordx2 v[80:81], v17, s[14:15] offset:3072 nt
	global_load_dwordx2 v[82:83], v17, s[14:15] offset:3584 nt
	global_load_dwordx4 v[116:119], v0, s[20:21] offset:0
	global_load_dwordx4 v[120:123], v0, s[20:21] offset:1024
	global_load_dwordx4 v[124:127], v0, s[20:21] offset:2048
	global_load_dwordx4 v[128:131], v0, s[20:21] offset:3072
	global_load_dwordx4 v[132:135], v1, s[20:21] offset:0
	global_load_dwordx4 v[136:139], v1, s[20:21] offset:1024
	global_load_dwordx4 v[140:143], v1, s[20:21] offset:2048
	global_load_dwordx4 v[144:147], v1, s[20:21] offset:3072
	global_load_dwordx4 v[84:87], v0, s[16:17] offset:0 nt
	global_load_dwordx4 v[88:91], v0, s[16:17] offset:1024 nt
	global_load_dwordx4 v[92:95], v0, s[16:17] offset:2048 nt
	global_load_dwordx4 v[96:99], v0, s[16:17] offset:3072 nt
	global_load_dwordx4 v[100:103], v1, s[16:17] offset:0 nt
	global_load_dwordx4 v[104:107], v1, s[16:17] offset:1024 nt
	global_load_dwordx4 v[108:111], v1, s[16:17] offset:2048 nt
	global_load_dwordx4 v[112:115], v1, s[16:17] offset:3072 nt
	global_load_dwordx4 v[148:151], v0, s[18:19] offset:0 nt
	global_load_dwordx4 v[152:155], v0, s[18:19] offset:1024 nt
	global_load_dwordx4 v[156:159], v0, s[18:19] offset:2048 nt
	global_load_dwordx4 v[160:163], v0, s[18:19] offset:3072 nt
	global_load_dwordx4 v[164:167], v1, s[18:19] offset:0 nt
	global_load_dwordx4 v[168:171], v1, s[18:19] offset:1024 nt
	global_load_dwordx4 v[172:175], v1, s[18:19] offset:2048 nt
	global_load_dwordx4 v[176:179], v1, s[18:19] offset:3072 nt
	s_waitcnt vmcnt(24)
; DI float lo16(unsigned u) { return __uint_as_float(u << 16); }
; DI float hi16(unsigned u) { return __uint_as_float(u & 0xFFFF0000u); }
; DI void post_phase(const P& p, int l, unsigned char* smem, int t0, int t1, int bstart, int bstride) {
;     ...
;         f32x4 y[8]; float ss = 0.f;
; #pragma unroll
;         for (int i = 0; i < 8; ++i) {
;             const u32x2 w = __builtin_nontemporal_load((const u32x2*)(yo + (size_t)row * DM + i * 256 + lane * 4));
;             y[i] = (f32x4){lo16(w.x), hi16(w.x), lo16(w.y), hi16(w.y)};
;             ss += y[i][0] * y[i][0] + y[i][1] * y[i][1] + y[i][2] * y[i][2] + y[i][3] * y[i][3];
;         }
;         ss = wave_sum(ss);
;         const float rstd = rsqrtf(ss * (1.f / 2048.f) + 1e-6f);
;         const float* md = mod + (size_t)(l * 5 + mr) * 6144;
;         float ss2 = 0.f;
; #pragma unroll
;         for (int i = 0; i < 8; ++i) {
;             const int j = i * 256 + lane * 4;
;             const f32x4 hv = __builtin_nontemporal_load((const f32x4*)(h + j)), gt = *(const f32x4*)(md + 4096 + j), nw = *(const f32x4*)(p.norm_post + l * DM + j);
; #pragma unroll
;             for (int e = 0; e < 4; ++e) { y[i][e] = hv[e] + gt[e] * (y[i][e] * rstd * nw[e]); ss2 += y[i][e] * y[i][e]; }
;             __builtin_nontemporal_store(y[i], (f32x4*)(hdst + j));
;         }
	v_lshlrev_b32_e32 v212, 16, v52
	v_and_b32_e32 v213, 0xffff0000, v52
	v_lshlrev_b32_e32 v214, 16, v53
	v_and_b32_e32 v215, 0xffff0000, v53
	v_mul_f32_e32 v9, v212, v212
	v_mul_f32_e32 v15, v213, v213
	v_fmac_f32_e32 v9, v214, v214
	v_fmac_f32_e32 v15, v215, v215
	v_lshlrev_b32_e32 v212, 16, v54
	v_and_b32_e32 v213, 0xffff0000, v54
	v_lshlrev_b32_e32 v214, 16, v55
	v_and_b32_e32 v215, 0xffff0000, v55
	v_fmac_f32_e32 v9, v212, v212
	v_fmac_f32_e32 v15, v213, v213
	v_fmac_f32_e32 v9, v214, v214
	v_fmac_f32_e32 v15, v215, v215
	v_lshlrev_b32_e32 v212, 16, v56
	v_and_b32_e32 v213, 0xffff0000, v56
	v_lshlrev_b32_e32 v214, 16, v57
	v_and_b32_e32 v215, 0xffff0000, v57
	v_fmac_f32_e32 v9, v212, v212
	v_fmac_f32_e32 v15, v213, v213
	v_fmac_f32_e32 v9, v214, v214
	v_fmac_f32_e32 v15, v215, v215
	v_lshlrev_b32_e32 v212, 16, v58
	v_and_b32_e32 v213, 0xffff0000, v58
	v_lshlrev_b32_e32 v214, 16, v59
	v_and_b32_e32 v215, 0xffff0000, v59
	v_fmac_f32_e32 v9, v212, v212
	v_fmac_f32_e32 v15, v213, v213
	v_fmac_f32_e32 v9, v214, v214
	v_fmac_f32_e32 v15, v215, v215
	v_lshlrev_b32_e32 v212, 16, v60
	v_and_b32_e32 v213, 0xffff0000, v60
	v_lshlrev_b32_e32 v214, 16, v61
	v_and_b32_e32 v215, 0xffff0000, v61
	v_fmac_f32_e32 v9, v212, v212
	v_fmac_f32_e32 v15, v213, v213
	v_fmac_f32_e32 v9, v214, v214
	v_fmac_f32_e32 v15, v215, v215
	v_lshlrev_b32_e32 v212, 16, v62
	v_and_b32_e32 v213, 0xffff0000, v62
	v_lshlrev_b32_e32 v214, 16, v63
	v_and_b32_e32 v215, 0xffff0000, v63
	v_fmac_f32_e32 v9, v212, v212
	v_fmac_f32_e32 v15, v213, v213
	v_fmac_f32_e32 v9, v214, v214
	v_fmac_f32_e32 v15, v215, v215
	v_lshlrev_b32_e32 v212, 16, v64
	v_and_b32_e32 v213, 0xffff0000, v64
	v_lshlrev_b32_e32 v214, 16, v65
	v_and_b32_e32 v215, 0xffff0000, v65
	v_fmac_f32_e32 v9, v212, v212
	v_fmac_f32_e32 v15, v213, v213
	v_fmac_f32_e32 v9, v214, v214
	v_fmac_f32_e32 v15, v215, v215
	v_lshlrev_b32_e32 v212, 16, v66
	v_and_b32_e32 v213, 0xffff0000, v66
	v_lshlrev_b32_e32 v214, 16, v67
	v_and_b32_e32 v215, 0xffff0000, v67
	v_fmac_f32_e32 v9, v212, v212
	v_fmac_f32_e32 v15, v213, v213
	v_fmac_f32_e32 v9, v214, v214
	v_fmac_f32_e32 v15, v215, v215
	v_add_f32_e32 v9, v9, v15
	v_lshlrev_b32_e32 v212, 16, v68
	v_and_b32_e32 v213, 0xffff0000, v68
	v_lshlrev_b32_e32 v214, 16, v69
	v_and_b32_e32 v215, 0xffff0000, v69
	v_mul_f32_e32 v10, v212, v212
	v_mul_f32_e32 v16, v213, v213
	v_fmac_f32_e32 v10, v214, v214
	v_fmac_f32_e32 v16, v215, v215
	v_lshlrev_b32_e32 v212, 16, v70
	v_and_b32_e32 v213, 0xffff0000, v70
	v_lshlrev_b32_e32 v214, 16, v71
	v_and_b32_e32 v215, 0xffff0000, v71
	v_fmac_f32_e32 v10, v212, v212
	v_fmac_f32_e32 v16, v213, v213
	v_fmac_f32_e32 v10, v214, v214
	v_fmac_f32_e32 v16, v215, v215
	v_lshlrev_b32_e32 v212, 16, v72
	v_and_b32_e32 v213, 0xffff0000, v72
	v_lshlrev_b32_e32 v214, 16, v73
	v_and_b32_e32 v215, 0xffff0000, v73
	v_fmac_f32_e32 v10, v212, v212
	v_fmac_f32_e32 v16, v213, v213
	v_fmac_f32_e32 v10, v214, v214
	v_fmac_f32_e32 v16, v215, v215
	v_lshlrev_b32_e32 v212, 16, v74
	v_and_b32_e32 v213, 0xffff0000, v74
	v_lshlrev_b32_e32 v214, 16, v75
	v_and_b32_e32 v215, 0xffff0000, v75
	v_fmac_f32_e32 v10, v212, v212
	v_fmac_f32_e32 v16, v213, v213
	v_fmac_f32_e32 v10, v214, v214
	v_fmac_f32_e32 v16, v215, v215
	v_lshlrev_b32_e32 v212, 16, v76
	v_and_b32_e32 v213, 0xffff0000, v76
	v_lshlrev_b32_e32 v214, 16, v77
	v_and_b32_e32 v215, 0xffff0000, v77
	v_fmac_f32_e32 v10, v212, v212
	v_fmac_f32_e32 v16, v213, v213
	v_fmac_f32_e32 v10, v214, v214
	v_fmac_f32_e32 v16, v215, v215
	v_lshlrev_b32_e32 v212, 16, v78
	v_and_b32_e32 v213, 0xffff0000, v78
	v_lshlrev_b32_e32 v214, 16, v79
	v_and_b32_e32 v215, 0xffff0000, v79
	v_fmac_f32_e32 v10, v212, v212
	v_fmac_f32_e32 v16, v213, v213
	v_fmac_f32_e32 v10, v214, v214
	v_fmac_f32_e32 v16, v215, v215
	v_lshlrev_b32_e32 v212, 16, v80
	v_and_b32_e32 v213, 0xffff0000, v80
	v_lshlrev_b32_e32 v214, 16, v81
	v_and_b32_e32 v215, 0xffff0000, v81
	v_fmac_f32_e32 v10, v212, v212
	v_fmac_f32_e32 v16, v213, v213
	v_fmac_f32_e32 v10, v214, v214
	v_fmac_f32_e32 v16, v215, v215
	v_lshlrev_b32_e32 v212, 16, v82
	v_and_b32_e32 v213, 0xffff0000, v82
	v_lshlrev_b32_e32 v214, 16, v83
	v_and_b32_e32 v215, 0xffff0000, v83
	v_fmac_f32_e32 v10, v212, v212
	v_fmac_f32_e32 v16, v213, v213
	v_fmac_f32_e32 v10, v214, v214
	v_fmac_f32_e32 v16, v215, v215
	v_add_f32_e32 v10, v10, v16
	ds_bpermute_b32 v11, v3, v9
	ds_bpermute_b32 v12, v3, v10
	s_waitcnt lgkmcnt(1)
	v_add_f32_e32 v9, v9, v11
	s_waitcnt lgkmcnt(0)
	v_add_f32_e32 v10, v10, v12
	ds_bpermute_b32 v11, v4, v9
	ds_bpermute_b32 v12, v4, v10
	s_waitcnt lgkmcnt(1)
	v_add_f32_e32 v9, v9, v11
	s_waitcnt lgkmcnt(0)
	v_add_f32_e32 v10, v10, v12
	ds_bpermute_b32 v11, v5, v9
	ds_bpermute_b32 v12, v5, v10
	s_waitcnt lgkmcnt(1)
	v_add_f32_e32 v9, v9, v11
	s_waitcnt lgkmcnt(0)
	v_add_f32_e32 v10, v10, v12
	ds_bpermute_b32 v11, v6, v9
	ds_bpermute_b32 v12, v6, v10
	s_waitcnt lgkmcnt(1)
	v_add_f32_e32 v9, v9, v11
	s_waitcnt lgkmcnt(0)
	v_add_f32_e32 v10, v10, v12
	ds_bpermute_b32 v11, v7, v9
	ds_bpermute_b32 v12, v7, v10
	s_waitcnt lgkmcnt(1)
	v_add_f32_e32 v9, v9, v11
	s_waitcnt lgkmcnt(0)
	v_add_f32_e32 v10, v10, v12
	ds_bpermute_b32 v11, v8, v9
	ds_bpermute_b32 v12, v8, v10
	s_waitcnt lgkmcnt(1)
	v_add_f32_e32 v9, v9, v11
	s_waitcnt lgkmcnt(0)
	v_add_f32_e32 v10, v10, v12
	v_mov_b32_e32 v11, 0x358637bd
	v_fmamk_f32 v9, v9, 0x3a000000, v11
	v_fmamk_f32 v10, v10, 0x3a000000, v11
	v_rsq_f32_e32 v13, v9
	v_rsq_f32_e32 v14, v10
	s_nop 0
	v_lshlrev_b32_e32 v212, 16, v52
	v_and_b32_e32 v213, 0xffff0000, v52
	v_lshlrev_b32_e32 v214, 16, v53
	v_and_b32_e32 v215, 0xffff0000, v53
	v_mul_f32_e32 v212, v13, v212
	v_mul_f32_e32 v213, v13, v213
	v_mul_f32_e32 v214, v13, v214
	v_mul_f32_e32 v215, v13, v215
	v_mul_f32_e32 v212, v20, v212
	v_mul_f32_e32 v213, v21, v213
	v_mul_f32_e32 v214, v22, v214
	v_mul_f32_e32 v215, v23, v215
	s_waitcnt vmcnt(15)
; DI void post_phase(const P& p, int l, unsigned char* smem, int t0, int t1, int bstart, int bstride) {
;     ...
; #pragma unroll
;         for (int i = 0; i < 8; ++i) {
;             const int j = i * 256 + lane * 4;
;             const f32x4 hv = __builtin_nontemporal_load((const f32x4*)(h + j)), gt = *(const f32x4*)(md + 4096 + j), nw = *(const f32x4*)(p.norm_post + l * DM + j);
; #pragma unroll
;             for (int e = 0; e < 4; ++e) { y[i][e] = hv[e] + gt[e] * (y[i][e] * rstd * nw[e]); ss2 += y[i][e] * y[i][e]; }
;             __builtin_nontemporal_store(y[i], (f32x4*)(hdst + j));
;         }
	v_fma_f32 v84, v116, v212, v84
	v_fma_f32 v85, v117, v213, v85
	v_fma_f32 v86, v118, v214, v86
	v_fma_f32 v87, v119, v215, v87
	global_store_dwordx4 v0, v[84:87], s[16:17] offset:0 sc1
	v_lshlrev_b32_e32 v212, 16, v54
	v_and_b32_e32 v213, 0xffff0000, v54
	v_lshlrev_b32_e32 v214, 16, v55
	v_and_b32_e32 v215, 0xffff0000, v55
	v_mul_f32_e32 v212, v13, v212
	v_mul_f32_e32 v213, v13, v213
	v_mul_f32_e32 v214, v13, v214
	v_mul_f32_e32 v215, v13, v215
	v_mul_f32_e32 v212, v24, v212
	v_mul_f32_e32 v213, v25, v213
	v_mul_f32_e32 v214, v26, v214
	v_mul_f32_e32 v215, v27, v215
	s_waitcnt vmcnt(15)
	v_fma_f32 v88, v120, v212, v88
	v_fma_f32 v89, v121, v213, v89
	v_fma_f32 v90, v122, v214, v90
	v_fma_f32 v91, v123, v215, v91
	global_store_dwordx4 v0, v[88:91], s[16:17] offset:1024 sc1
	v_lshlrev_b32_e32 v212, 16, v56
	v_and_b32_e32 v213, 0xffff0000, v56
	v_lshlrev_b32_e32 v214, 16, v57
	v_and_b32_e32 v215, 0xffff0000, v57
	v_mul_f32_e32 v212, v13, v212
	v_mul_f32_e32 v213, v13, v213
	v_mul_f32_e32 v214, v13, v214
	v_mul_f32_e32 v215, v13, v215
	v_mul_f32_e32 v212, v28, v212
	v_mul_f32_e32 v213, v29, v213
	v_mul_f32_e32 v214, v30, v214
	v_mul_f32_e32 v215, v31, v215
	s_waitcnt vmcnt(15)
	v_fma_f32 v92, v124, v212, v92
	v_fma_f32 v93, v125, v213, v93
	v_fma_f32 v94, v126, v214, v94
	v_fma_f32 v95, v127, v215, v95
	global_store_dwordx4 v0, v[92:95], s[16:17] offset:2048 sc1
	v_lshlrev_b32_e32 v212, 16, v58
	v_and_b32_e32 v213, 0xffff0000, v58
	v_lshlrev_b32_e32 v214, 16, v59
	v_and_b32_e32 v215, 0xffff0000, v59
	v_mul_f32_e32 v212, v13, v212
	v_mul_f32_e32 v213, v13, v213
	v_mul_f32_e32 v214, v13, v214
	v_mul_f32_e32 v215, v13, v215
	v_mul_f32_e32 v212, v32, v212
	v_mul_f32_e32 v213, v33, v213
	v_mul_f32_e32 v214, v34, v214
	v_mul_f32_e32 v215, v35, v215
	s_waitcnt vmcnt(15)
	v_fma_f32 v96, v128, v212, v96
	v_fma_f32 v97, v129, v213, v97
	v_fma_f32 v98, v130, v214, v98
	v_fma_f32 v99, v131, v215, v99
	global_store_dwordx4 v0, v[96:99], s[16:17] offset:3072 sc1
	v_lshlrev_b32_e32 v212, 16, v60
	v_and_b32_e32 v213, 0xffff0000, v60
	v_lshlrev_b32_e32 v214, 16, v61
	v_and_b32_e32 v215, 0xffff0000, v61
	v_mul_f32_e32 v212, v13, v212
	v_mul_f32_e32 v213, v13, v213
	v_mul_f32_e32 v214, v13, v214
	v_mul_f32_e32 v215, v13, v215
	v_mul_f32_e32 v212, v36, v212
	v_mul_f32_e32 v213, v37, v213
	v_mul_f32_e32 v214, v38, v214
	v_mul_f32_e32 v215, v39, v215
	s_waitcnt vmcnt(15)
	v_fma_f32 v100, v132, v212, v100
	v_fma_f32 v101, v133, v213, v101
	v_fma_f32 v102, v134, v214, v102
	v_fma_f32 v103, v135, v215, v103
	global_store_dwordx4 v1, v[100:103], s[16:17] offset:0 sc1
	v_lshlrev_b32_e32 v212, 16, v62
	v_and_b32_e32 v213, 0xffff0000, v62
	v_lshlrev_b32_e32 v214, 16, v63
	v_and_b32_e32 v215, 0xffff0000, v63
	v_mul_f32_e32 v212, v13, v212
	v_mul_f32_e32 v213, v13, v213
	v_mul_f32_e32 v214, v13, v214
	v_mul_f32_e32 v215, v13, v215
	v_mul_f32_e32 v212, v40, v212
	v_mul_f32_e32 v213, v41, v213
	v_mul_f32_e32 v214, v42, v214
	v_mul_f32_e32 v215, v43, v215
	s_waitcnt vmcnt(15)
	v_fma_f32 v104, v136, v212, v104
	v_fma_f32 v105, v137, v213, v105
	v_fma_f32 v106, v138, v214, v106
	v_fma_f32 v107, v139, v215, v107
	global_store_dwordx4 v1, v[104:107], s[16:17] offset:1024 sc1
	v_lshlrev_b32_e32 v212, 16, v64
	v_and_b32_e32 v213, 0xffff0000, v64
	v_lshlrev_b32_e32 v214, 16, v65
	v_and_b32_e32 v215, 0xffff0000, v65
	v_mul_f32_e32 v212, v13, v212
	v_mul_f32_e32 v213, v13, v213
	v_mul_f32_e32 v214, v13, v214
	v_mul_f32_e32 v215, v13, v215
	v_mul_f32_e32 v212, v44, v212
	v_mul_f32_e32 v213, v45, v213
	v_mul_f32_e32 v214, v46, v214
	v_mul_f32_e32 v215, v47, v215
	s_waitcnt vmcnt(15)
	v_fma_f32 v108, v140, v212, v108
	v_fma_f32 v109, v141, v213, v109
	v_fma_f32 v110, v142, v214, v110
	v_fma_f32 v111, v143, v215, v111
	global_store_dwordx4 v1, v[108:111], s[16:17] offset:2048 sc1
	v_lshlrev_b32_e32 v212, 16, v66
	v_and_b32_e32 v213, 0xffff0000, v66
	v_lshlrev_b32_e32 v214, 16, v67
	v_and_b32_e32 v215, 0xffff0000, v67
	v_mul_f32_e32 v212, v13, v212
	v_mul_f32_e32 v213, v13, v213
	v_mul_f32_e32 v214, v13, v214
	v_mul_f32_e32 v215, v13, v215
	v_mul_f32_e32 v212, v48, v212
	v_mul_f32_e32 v213, v49, v213
	v_mul_f32_e32 v214, v50, v214
	v_mul_f32_e32 v215, v51, v215
	s_waitcnt vmcnt(15)
	v_fma_f32 v112, v144, v212, v112
	v_fma_f32 v113, v145, v213, v113
	v_fma_f32 v114, v146, v214, v114
	v_fma_f32 v115, v147, v215, v115
	global_store_dwordx4 v1, v[112:115], s[16:17] offset:3072 sc1
	v_lshlrev_b32_e32 v212, 16, v68
	v_and_b32_e32 v213, 0xffff0000, v68
	v_lshlrev_b32_e32 v214, 16, v69
	v_and_b32_e32 v215, 0xffff0000, v69
	v_mul_f32_e32 v212, v14, v212
	v_mul_f32_e32 v213, v14, v213
	v_mul_f32_e32 v214, v14, v214
	v_mul_f32_e32 v215, v14, v215
	v_mul_f32_e32 v212, v20, v212
	v_mul_f32_e32 v213, v21, v213
	v_mul_f32_e32 v214, v22, v214
	v_mul_f32_e32 v215, v23, v215
	s_waitcnt vmcnt(15)
; DI void post_phase(const P& p, int l, unsigned char* smem, int t0, int t1, int bstart, int bstride) {
;     ...
; #pragma unroll
;         for (int i = 0; i < 8; ++i) {
;             const int j = i * 256 + lane * 4;
;             const f32x4 hv = __builtin_nontemporal_load((const f32x4*)(h + j)), gt = *(const f32x4*)(md + 4096 + j), nw = *(const f32x4*)(p.norm_post + l * DM + j);
; #pragma unroll
;             for (int e = 0; e < 4; ++e) { y[i][e] = hv[e] + gt[e] * (y[i][e] * rstd * nw[e]); ss2 += y[i][e] * y[i][e]; }
;             __builtin_nontemporal_store(y[i], (f32x4*)(hdst + j));
;         }
	v_fma_f32 v148, v116, v212, v148
	v_fma_f32 v149, v117, v213, v149
	v_fma_f32 v150, v118, v214, v150
	v_fma_f32 v151, v119, v215, v151
	global_store_dwordx4 v0, v[148:151], s[18:19] offset:0 sc1
	v_lshlrev_b32_e32 v212, 16, v70
	v_and_b32_e32 v213, 0xffff0000, v70
	v_lshlrev_b32_e32 v214, 16, v71
	v_and_b32_e32 v215, 0xffff0000, v71
	v_mul_f32_e32 v212, v14, v212
	v_mul_f32_e32 v213, v14, v213
	v_mul_f32_e32 v214, v14, v214
	v_mul_f32_e32 v215, v14, v215
	v_mul_f32_e32 v212, v24, v212
	v_mul_f32_e32 v213, v25, v213
	v_mul_f32_e32 v214, v26, v214
	v_mul_f32_e32 v215, v27, v215
	s_waitcnt vmcnt(15)
	v_fma_f32 v152, v120, v212, v152
	v_fma_f32 v153, v121, v213, v153
	v_fma_f32 v154, v122, v214, v154
	v_fma_f32 v155, v123, v215, v155
	global_store_dwordx4 v0, v[152:155], s[18:19] offset:1024 sc1
	v_lshlrev_b32_e32 v212, 16, v72
	v_and_b32_e32 v213, 0xffff0000, v72
	v_lshlrev_b32_e32 v214, 16, v73
	v_and_b32_e32 v215, 0xffff0000, v73
	v_mul_f32_e32 v212, v14, v212
	v_mul_f32_e32 v213, v14, v213
	v_mul_f32_e32 v214, v14, v214
	v_mul_f32_e32 v215, v14, v215
	v_mul_f32_e32 v212, v28, v212
	v_mul_f32_e32 v213, v29, v213
	v_mul_f32_e32 v214, v30, v214
	v_mul_f32_e32 v215, v31, v215
	s_waitcnt vmcnt(15)
	v_fma_f32 v156, v124, v212, v156
	v_fma_f32 v157, v125, v213, v157
	v_fma_f32 v158, v126, v214, v158
	v_fma_f32 v159, v127, v215, v159
	global_store_dwordx4 v0, v[156:159], s[18:19] offset:2048 sc1
	v_lshlrev_b32_e32 v212, 16, v74
	v_and_b32_e32 v213, 0xffff0000, v74
	v_lshlrev_b32_e32 v214, 16, v75
	v_and_b32_e32 v215, 0xffff0000, v75
	v_mul_f32_e32 v212, v14, v212
	v_mul_f32_e32 v213, v14, v213
	v_mul_f32_e32 v214, v14, v214
	v_mul_f32_e32 v215, v14, v215
	v_mul_f32_e32 v212, v32, v212
	v_mul_f32_e32 v213, v33, v213
	v_mul_f32_e32 v214, v34, v214
	v_mul_f32_e32 v215, v35, v215
	s_waitcnt vmcnt(15)
	v_fma_f32 v160, v128, v212, v160
	v_fma_f32 v161, v129, v213, v161
	v_fma_f32 v162, v130, v214, v162
	v_fma_f32 v163, v131, v215, v163
	global_store_dwordx4 v0, v[160:163], s[18:19] offset:3072 sc1
	v_lshlrev_b32_e32 v212, 16, v76
	v_and_b32_e32 v213, 0xffff0000, v76
	v_lshlrev_b32_e32 v214, 16, v77
	v_and_b32_e32 v215, 0xffff0000, v77
	v_mul_f32_e32 v212, v14, v212
	v_mul_f32_e32 v213, v14, v213
	v_mul_f32_e32 v214, v14, v214
	v_mul_f32_e32 v215, v14, v215
	v_mul_f32_e32 v212, v36, v212
	v_mul_f32_e32 v213, v37, v213
	v_mul_f32_e32 v214, v38, v214
	v_mul_f32_e32 v215, v39, v215
	s_waitcnt vmcnt(15)
	v_fma_f32 v164, v132, v212, v164
	v_fma_f32 v165, v133, v213, v165
	v_fma_f32 v166, v134, v214, v166
	v_fma_f32 v167, v135, v215, v167
	global_store_dwordx4 v1, v[164:167], s[18:19] offset:0 sc1
	v_lshlrev_b32_e32 v212, 16, v78
	v_and_b32_e32 v213, 0xffff0000, v78
	v_lshlrev_b32_e32 v214, 16, v79
	v_and_b32_e32 v215, 0xffff0000, v79
	v_mul_f32_e32 v212, v14, v212
	v_mul_f32_e32 v213, v14, v213
	v_mul_f32_e32 v214, v14, v214
	v_mul_f32_e32 v215, v14, v215
	v_mul_f32_e32 v212, v40, v212
	v_mul_f32_e32 v213, v41, v213
	v_mul_f32_e32 v214, v42, v214
	v_mul_f32_e32 v215, v43, v215
	s_waitcnt vmcnt(15)
	v_fma_f32 v168, v136, v212, v168
	v_fma_f32 v169, v137, v213, v169
	v_fma_f32 v170, v138, v214, v170
	v_fma_f32 v171, v139, v215, v171
	global_store_dwordx4 v1, v[168:171], s[18:19] offset:1024 sc1
	v_lshlrev_b32_e32 v212, 16, v80
	v_and_b32_e32 v213, 0xffff0000, v80
	v_lshlrev_b32_e32 v214, 16, v81
	v_and_b32_e32 v215, 0xffff0000, v81
	v_mul_f32_e32 v212, v14, v212
	v_mul_f32_e32 v213, v14, v213
	v_mul_f32_e32 v214, v14, v214
	v_mul_f32_e32 v215, v14, v215
	v_mul_f32_e32 v212, v44, v212
	v_mul_f32_e32 v213, v45, v213
	v_mul_f32_e32 v214, v46, v214
	v_mul_f32_e32 v215, v47, v215
	s_waitcnt vmcnt(15)
	v_fma_f32 v172, v140, v212, v172
	v_fma_f32 v173, v141, v213, v173
	v_fma_f32 v174, v142, v214, v174
	v_fma_f32 v175, v143, v215, v175
	global_store_dwordx4 v1, v[172:175], s[18:19] offset:2048 sc1
	v_lshlrev_b32_e32 v212, 16, v82
	v_and_b32_e32 v213, 0xffff0000, v82
	v_lshlrev_b32_e32 v214, 16, v83
	v_and_b32_e32 v215, 0xffff0000, v83
	v_mul_f32_e32 v212, v14, v212
	v_mul_f32_e32 v213, v14, v213
	v_mul_f32_e32 v214, v14, v214
	v_mul_f32_e32 v215, v14, v215
	v_mul_f32_e32 v212, v48, v212
	v_mul_f32_e32 v213, v49, v213
	v_mul_f32_e32 v214, v50, v214
	v_mul_f32_e32 v215, v51, v215
	s_waitcnt vmcnt(15)
	v_fma_f32 v176, v144, v212, v176
	v_fma_f32 v177, v145, v213, v177
	v_fma_f32 v178, v146, v214, v178
	v_fma_f32 v179, v147, v215, v179
	global_store_dwordx4 v1, v[176:179], s[18:19] offset:3072 sc1
	s_branch .LBB0_805
